# attention: first two P.V MFMAs issued ahead of the row-max VALU chain (MFMA/VALU interleave at the phase A->B seam)
# baseline (speedup 1.0000x reference)
.LBB0_878:
	v_add_u32_e32 v183, s96, v209
	ds_read_b64_tr_b16 v[178:179], v183 offset:24576
	ds_read_b64_tr_b16 v[180:181], v183 offset:25088
	v_mfma_f32_32x32x16_bf16 v[98:113], v[82:85], v[142:145], v[34:49]
	v_add_f32_e32 v86, v66, v67
	v_add_f32_e32 v86, v68, v86
	v_add_f32_e32 v86, v69, v86
	v_add_f32_e32 v86, v70, v86
	v_add_f32_e32 v86, v71, v86
	v_cvt_pk_bf16_f32 v158, v66, v67
	v_cvt_pk_bf16_f32 v159, v68, v69
	ds_read_b64_tr_b16 v[174:175], v183 offset:28672
	ds_read_b64_tr_b16 v[176:177], v183 offset:29184
	v_add_f32_e32 v66, v72, v86
	v_mfma_f32_32x32x16_bf16 v[82:97], v[170:173], v[142:145], v[34:49]
	v_add_f32_e32 v66, v73, v66
	v_add_f32_e32 v66, v74, v66
	v_add_f32_e32 v66, v75, v66
	v_cvt_pk_bf16_f32 v160, v70, v71
	v_cvt_pk_bf16_f32 v161, v72, v73
	ds_read_b64_tr_b16 v[170:171], v183 offset:25600
	ds_read_b64_tr_b16 v[172:173], v183 offset:26112
	v_mfma_f32_32x32x16_bf16 v[98:113], v[166:169], v[138:141], v[98:113]
	v_add_f32_e32 v66, v76, v66
	v_add_f32_e32 v66, v77, v66
	v_add_f32_e32 v66, v78, v66
	v_add_f32_e32 v66, v79, v66
	v_cvt_pk_bf16_f32 v154, v74, v75
	v_cvt_pk_bf16_f32 v155, v76, v77
	ds_read_b64_tr_b16 v[74:75], v183 offset:29696
	ds_read_b64_tr_b16 v[76:77], v183 offset:30208
	v_mfma_f32_32x32x16_bf16 v[82:97], v[162:165], v[138:141], v[82:97]
	v_add_f32_e32 v66, v80, v66
	v_add_f32_e32 v66, v81, v66
	v_add_f32_e32 v66, v50, v66
	v_add_f32_e32 v66, v51, v66
	v_cvt_pk_bf16_f32 v156, v78, v79
	v_cvt_pk_bf16_f32 v157, v80, v81
	ds_read_b64_tr_b16 v[70:71], v183 offset:26624
	ds_read_b64_tr_b16 v[72:73], v183 offset:27136
	v_mfma_f32_32x32x16_bf16 v[98:113], v[126:129], v[134:137], v[98:113]
	v_add_f32_e32 v66, v52, v66
	v_add_f32_e32 v66, v53, v66
	v_add_f32_e32 v66, v54, v66
	v_add_f32_e32 v78, v55, v66
	v_cvt_pk_bf16_f32 v150, v50, v51
	v_cvt_pk_bf16_f32 v151, v52, v53
	ds_read_b64_tr_b16 v[66:67], v183 offset:30720
	ds_read_b64_tr_b16 v[68:69], v183 offset:31232
	v_mfma_f32_32x32x16_bf16 v[82:97], v[122:125], v[134:137], v[82:97]
	v_add_f32_e32 v50, v56, v78
	v_add_f32_e32 v50, v57, v50
	v_add_f32_e32 v50, v58, v50
	v_add_f32_e32 v50, v59, v50
	v_cvt_pk_bf16_f32 v152, v54, v55
	v_cvt_pk_bf16_f32 v153, v56, v57
	ds_read_b64_tr_b16 v[54:55], v183 offset:27648
	ds_read_b64_tr_b16 v[56:57], v183 offset:28160
	v_mfma_f32_32x32x16_bf16 v[98:113], v[118:121], v[130:133], v[98:113]
	v_add_f32_e32 v50, v60, v50
	v_add_f32_e32 v50, v61, v50
	v_add_f32_e32 v50, v62, v50
	v_add_f32_e32 v78, v63, v50
	v_cvt_pk_bf16_f32 v146, v58, v59
	v_cvt_pk_bf16_f32 v147, v60, v61
	ds_read_b64_tr_b16 v[50:51], v183 offset:31744
	ds_read_b64_tr_b16 v[52:53], v183 offset:32256
	v_mfma_f32_32x32x16_bf16 v[82:97], v[114:117], v[130:133], v[82:97]
	v_add_f32_e32 v58, v64, v78
	v_add_f32_e32 v58, v65, v58
	v_add_f32_e32 v60, 0, v58
	v_cvt_pk_bf16_f32 v148, v62, v63
	v_cvt_pk_bf16_f32 v149, v64, v65
	v_lshl_add_u64 v[58:59], v[196:197], 0, s[30:31]
	s_add_i32 s15, s64, s94
	s_mov_b32 s19, m0
	s_mov_b32 m0, s15
	s_nop 0
	global_load_lds_dwordx4 v[58:59], off
	s_mov_b32 m0, s19
	v_lshl_add_u64 v[58:59], v[188:189], 0, s[26:27]
	s_add_i32 s15, s18, s93
	s_mov_b32 s19, m0
	s_mov_b32 m0, s15
	s_nop 0
	global_load_lds_dwordx4 v[58:59], off
	s_mov_b32 m0, s19
	s_waitcnt lgkmcnt(14)
	v_mfma_f32_32x32x16_bf16 v[2:17], v[158:161], v[178:181], v[2:17]
	s_waitcnt lgkmcnt(12)
	v_mfma_f32_32x32x16_bf16 v[18:33], v[158:161], v[174:177], v[18:33]
	v_max_f32_e32 v58, v99, v99
	v_max_f32_e32 v59, v98, v98
	v_max_f32_e32 v58, v59, v58
	v_max3_f32 v59, v100, v101, v83
	v_max3_f32 v58, v58, v82, v84
	v_max3_f32 v58, v58, v85, v102
	v_max3_f32 v59, v59, v104, v105
	v_max3_f32 v58, v58, v103, v86
	v_max3_f32 v59, v59, v88, v89
	v_max3_f32 v58, v58, v87, v106
	v_max3_f32 v59, v59, v108, v109
	v_max3_f32 v58, v58, v107, v90
	v_max3_f32 v59, v59, v92, v93
	v_max3_f32 v58, v58, v91, v110
	v_max3_f32 v59, v59, v112, v113
	v_max3_f32 v58, v58, v111, v94
	v_max3_f32 v59, v59, v96, v97
	v_max3_f32 v58, v58, v95, v59
	v_mov_b32_e32 v59, v58
	s_nop 1
	v_permlane32_swap_b32_e32 v58, v59
	v_max_f32_e32 v59, v59, v59
	v_max_f32_e32 v58, v58, v58
	v_max_f32_e32 v58, v58, v59
	v_cmp_lt_f32_e32 vcc, s83, v58
	s_cmp_lg_u64 vcc, 0
	v_add_f32_e32 v213, v182, v60
	s_cselect_b64 s[60:61], -1, 0
	s_cbranch_vccnz .LBB0_886
.LBB0_879:
	v_exp_f32_e32 v98, v98
	v_exp_f32_e32 v99, v99
	v_exp_f32_e32 v100, v100
	v_exp_f32_e32 v101, v101
	v_exp_f32_e32 v102, v102
	v_exp_f32_e32 v103, v103
	v_exp_f32_e32 v104, v104
	v_exp_f32_e32 v105, v105
	v_add_u32_e32 v62, s18, v211
	ds_read_b128 v[58:61], v62
	ds_read_b128 v[114:117], v62 offset:512
	s_waitcnt lgkmcnt(12)
	v_mfma_f32_32x32x16_bf16 v[2:17], v[154:157], v[170:173], v[2:17]
	v_exp_f32_e32 v106, v106
	v_exp_f32_e32 v107, v107
	v_exp_f32_e32 v108, v108
	v_exp_f32_e32 v109, v109
	ds_read_b128 v[182:185], v62 offset:2048
	ds_read_b128 v[174:177], v62 offset:2560
	s_waitcnt lgkmcnt(12)
	v_mfma_f32_32x32x16_bf16 v[18:33], v[154:157], v[74:77], v[18:33]
	v_exp_f32_e32 v110, v110
	v_exp_f32_e32 v111, v111
	v_exp_f32_e32 v112, v112
	v_exp_f32_e32 v113, v113
	ds_read_b128 v[178:181], v62 offset:4096
	ds_read_b128 v[166:169], v62 offset:4608
	s_waitcnt lgkmcnt(12)
	v_mfma_f32_32x32x16_bf16 v[2:17], v[150:153], v[70:73], v[2:17]
	v_exp_f32_e32 v82, v82
	v_exp_f32_e32 v83, v83
	v_exp_f32_e32 v84, v84
	v_exp_f32_e32 v85, v85
	ds_read_b128 v[170:173], v62 offset:6144
	ds_read_b128 v[162:165], v62 offset:6656
	s_waitcnt lgkmcnt(12)
	v_mfma_f32_32x32x16_bf16 v[18:33], v[150:153], v[66:69], v[18:33]
	v_exp_f32_e32 v86, v86
	v_exp_f32_e32 v87, v87
	v_exp_f32_e32 v88, v88
	v_exp_f32_e32 v89, v89
	s_waitcnt lgkmcnt(10)
	v_mfma_f32_32x32x16_bf16 v[2:17], v[146:149], v[54:57], v[2:17]
	v_exp_f32_e32 v90, v90
	v_exp_f32_e32 v91, v91
	v_exp_f32_e32 v92, v92
	v_exp_f32_e32 v93, v93
	s_waitcnt lgkmcnt(8)
	v_mfma_f32_32x32x16_bf16 v[18:33], v[146:149], v[50:53], v[18:33]
	v_exp_f32_e32 v94, v94
	v_exp_f32_e32 v95, v95
	v_exp_f32_e32 v96, v96
	v_exp_f32_e32 v97, v97
	s_waitcnt vmcnt(2) lgkmcnt(0)
	s_barrier
	s_andn2_b64 vcc, exec, s[60:61]
	s_cbranch_vccnz .LBB0_881
	s_waitcnt lgkmcnt(0)
	v_add_u32_e32 v66, s92, v212
	ds_read_b128 v[50:53], v66 offset:49248
	ds_read_b128 v[54:57], v66 offset:49216
	ds_read_b128 v[62:65], v66 offset:49184
	ds_read_b128 v[66:69], v66 offset:49152
	s_waitcnt lgkmcnt(3)
	v_pk_mul_f32 v[14:15], v[14:15], v[50:51]
	s_waitcnt lgkmcnt(2)
	v_pk_mul_f32 v[10:11], v[10:11], v[54:55]
	s_waitcnt lgkmcnt(1)
	v_pk_mul_f32 v[6:7], v[6:7], v[62:63]
	v_pk_mul_f32 v[16:17], v[16:17], v[52:53]
	v_pk_mul_f32 v[12:13], v[12:13], v[56:57]
	v_pk_mul_f32 v[8:9], v[8:9], v[64:65]
	s_waitcnt lgkmcnt(0)
	v_pk_mul_f32 v[4:5], v[4:5], v[68:69]
	v_pk_mul_f32 v[2:3], v[2:3], v[66:67]
	v_pk_mul_f32 v[30:31], v[30:31], v[50:51]
	v_pk_mul_f32 v[26:27], v[26:27], v[54:55]
	v_pk_mul_f32 v[22:23], v[22:23], v[62:63]
	v_pk_mul_f32 v[32:33], v[32:33], v[52:53]
	v_pk_mul_f32 v[28:29], v[28:29], v[56:57]
	v_pk_mul_f32 v[24:25], v[24:25], v[64:65]
	v_pk_mul_f32 v[20:21], v[20:21], v[68:69]
	v_pk_mul_f32 v[18:19], v[18:19], v[66:67]
.LBB0_881:
	s_add_i32 s15, s18, 0x2000
	s_cmpk_lg_i32 s18, 0x4000
	s_cselect_b32 s65, s15, 0
	v_add_u32_e32 v214, s64, v209
	ds_read_b64_tr_b16 v[126:127], v214 offset:24576
	ds_read_b64_tr_b16 v[128:129], v214 offset:25088
	v_mfma_f32_32x32x16_bf16 v[66:81], v[58:61], v[142:145], v[34:49]
	v_add_f32_e32 v50, v98, v99
	v_add_f32_e32 v50, v100, v50
	v_add_f32_e32 v50, v101, v50
	v_add_f32_e32 v50, v102, v50
	v_add_f32_e32 v50, v103, v50
	v_cvt_pk_bf16_f32 v158, v98, v99
	v_cvt_pk_bf16_f32 v159, v100, v101
	ds_read_b64_tr_b16 v[122:123], v214 offset:28672
	ds_read_b64_tr_b16 v[124:125], v214 offset:29184
	v_add_f32_e32 v50, v104, v50
	v_add_f32_e32 v50, v105, v50
	v_add_f32_e32 v50, v106, v50
	v_add_f32_e32 v98, v107, v50
	v_mfma_f32_32x32x16_bf16 v[50:65], v[114:117], v[142:145], v[34:49]
	v_cvt_pk_bf16_f32 v160, v102, v103
	v_cvt_pk_bf16_f32 v161, v104, v105
	ds_read_b64_tr_b16 v[118:119], v214 offset:25600
	ds_read_b64_tr_b16 v[120:121], v214 offset:26112
	v_mfma_f32_32x32x16_bf16 v[66:81], v[182:185], v[138:141], v[66:81]
	v_add_f32_e32 v98, v108, v98
	v_add_f32_e32 v98, v109, v98
	v_add_f32_e32 v98, v110, v98
	v_add_f32_e32 v98, v111, v98
	v_cvt_pk_bf16_f32 v154, v106, v107
	v_cvt_pk_bf16_f32 v155, v108, v109
	ds_read_b64_tr_b16 v[114:115], v214 offset:29696
	ds_read_b64_tr_b16 v[116:117], v214 offset:30208
	v_mfma_f32_32x32x16_bf16 v[50:65], v[174:177], v[138:141], v[50:65]
	v_add_f32_e32 v98, v112, v98
	v_add_f32_e32 v98, v113, v98
	v_add_f32_e32 v98, v82, v98
	v_add_f32_e32 v98, v83, v98
	v_cvt_pk_bf16_f32 v156, v110, v111
	v_cvt_pk_bf16_f32 v157, v112, v113
	ds_read_b64_tr_b16 v[106:107], v214 offset:26624
	ds_read_b64_tr_b16 v[108:109], v214 offset:27136
	v_mfma_f32_32x32x16_bf16 v[66:81], v[178:181], v[134:137], v[66:81]
	v_add_f32_e32 v98, v84, v98
	v_add_f32_e32 v98, v85, v98
	v_add_f32_e32 v98, v86, v98
	v_add_f32_e32 v98, v87, v98
	v_cvt_pk_bf16_f32 v150, v82, v83
	v_cvt_pk_bf16_f32 v151, v84, v85
	ds_read_b64_tr_b16 v[102:103], v214 offset:30720
	ds_read_b64_tr_b16 v[104:105], v214 offset:31232
	v_mfma_f32_32x32x16_bf16 v[50:65], v[166:169], v[134:137], v[50:65]
	v_add_f32_e32 v82, v88, v98
	v_add_f32_e32 v82, v89, v82
	v_add_f32_e32 v82, v90, v82
	v_add_f32_e32 v82, v91, v82
	v_cvt_pk_bf16_f32 v152, v86, v87
	v_cvt_pk_bf16_f32 v153, v88, v89
	ds_read_b64_tr_b16 v[98:99], v214 offset:27648
	ds_read_b64_tr_b16 v[100:101], v214 offset:28160
	v_mfma_f32_32x32x16_bf16 v[66:81], v[170:173], v[130:133], v[66:81]
	v_add_f32_e32 v82, v92, v82
	v_add_f32_e32 v82, v93, v82
	v_add_f32_e32 v82, v94, v82
	v_add_f32_e32 v82, v95, v82
	v_cvt_pk_bf16_f32 v146, v90, v91
	v_cvt_pk_bf16_f32 v147, v92, v93
	ds_read_b64_tr_b16 v[86:87], v214 offset:31744
	ds_read_b64_tr_b16 v[88:89], v214 offset:32256
	v_mfma_f32_32x32x16_bf16 v[50:65], v[162:165], v[130:133], v[50:65]
	v_add_f32_e32 v82, v96, v82
	v_add_f32_e32 v82, v97, v82
	v_add_f32_e32 v84, 0, v82
	v_cvt_pk_bf16_f32 v148, v94, v95
	v_cvt_pk_bf16_f32 v149, v96, v97
	v_lshl_add_u64 v[82:83], v[196:197], 0, s[34:35]
	s_add_i32 s15, s18, s94
	s_mov_b32 s19, m0
	s_mov_b32 m0, s15
	s_nop 0
	global_load_lds_dwordx4 v[82:83], off
	s_mov_b32 m0, s19
	s_waitcnt lgkmcnt(14)
	v_mfma_f32_32x32x16_bf16 v[2:17], v[158:161], v[126:129], v[2:17]
	s_waitcnt lgkmcnt(12)
	v_mfma_f32_32x32x16_bf16 v[18:33], v[158:161], v[122:125], v[18:33]
	v_max_f32_e32 v82, v67, v67
	v_max_f32_e32 v83, v66, v66
	v_max_f32_e32 v82, v83, v82
	s_nop 1
	v_max3_f32 v83, v68, v69, v51
	v_max3_f32 v82, v82, v50, v52
	v_max3_f32 v82, v82, v53, v70
	v_max3_f32 v83, v83, v72, v73
	v_max3_f32 v82, v82, v71, v54
	v_max3_f32 v83, v83, v56, v57
	v_max3_f32 v82, v82, v55, v74
	v_max3_f32 v83, v83, v76, v77
	v_max3_f32 v82, v82, v75, v58
	v_max3_f32 v83, v83, v60, v61
	v_max3_f32 v82, v82, v59, v78
	v_max3_f32 v83, v83, v80, v81
	v_max3_f32 v82, v82, v79, v62
	v_max3_f32 v83, v83, v64, v65
	v_max3_f32 v82, v82, v63, v83
	v_mov_b32_e32 v83, v82
	s_nop 1
	v_permlane32_swap_b32_e32 v82, v83
	v_max_f32_e32 v83, v83, v83
	v_max_f32_e32 v82, v82, v82
	v_max_f32_e32 v82, v82, v83
	v_lshl_add_u64 v[188:189], v[188:189], 0, s[28:29]
	s_add_i32 s15, s65, s93
	s_mov_b32 s19, m0
	s_mov_b32 m0, s15
	s_nop 0
	global_load_lds_dwordx4 v[188:189], off
	s_mov_b32 m0, s19
	v_cmp_lt_f32_e32 vcc, s83, v82
	s_cmp_lg_u64 vcc, 0
	v_add_f32_e32 v182, v213, v84
	s_cselect_b64 s[60:61], -1, 0
	s_cbranch_vccnz .LBB0_889
.LBB0_882:
	v_exp_f32_e32 v66, v66
	v_exp_f32_e32 v67, v67
	v_exp_f32_e32 v68, v68
	v_exp_f32_e32 v69, v69
	v_exp_f32_e32 v70, v70
	v_exp_f32_e32 v71, v71
	v_exp_f32_e32 v72, v72
	v_exp_f32_e32 v73, v73
	v_add_u32_e32 v90, s65, v211
	ds_read_b128 v[82:85], v90
	ds_read_b128 v[170:173], v90 offset:512
	s_waitcnt lgkmcnt(12)
	v_mfma_f32_32x32x16_bf16 v[2:17], v[154:157], v[118:121], v[2:17]
	v_exp_f32_e32 v74, v74
	v_exp_f32_e32 v75, v75
	v_exp_f32_e32 v76, v76
	v_exp_f32_e32 v77, v77
	ds_read_b128 v[166:169], v90 offset:2048
	ds_read_b128 v[162:165], v90 offset:2560
	s_waitcnt lgkmcnt(12)
	v_mfma_f32_32x32x16_bf16 v[18:33], v[154:157], v[114:117], v[18:33]
	v_exp_f32_e32 v78, v78
	v_exp_f32_e32 v79, v79
	v_exp_f32_e32 v80, v80
	v_exp_f32_e32 v81, v81
	ds_read_b128 v[126:129], v90 offset:4096
	ds_read_b128 v[122:125], v90 offset:4608
	s_waitcnt lgkmcnt(12)
	v_mfma_f32_32x32x16_bf16 v[2:17], v[150:153], v[106:109], v[2:17]
	v_exp_f32_e32 v50, v50
	v_exp_f32_e32 v51, v51
	v_exp_f32_e32 v52, v52
	v_exp_f32_e32 v53, v53
	ds_read_b128 v[118:121], v90 offset:6144
	ds_read_b128 v[114:117], v90 offset:6656
	s_waitcnt lgkmcnt(12)
	v_mfma_f32_32x32x16_bf16 v[18:33], v[150:153], v[102:105], v[18:33]
	v_exp_f32_e32 v54, v54
	v_exp_f32_e32 v55, v55
	v_exp_f32_e32 v56, v56
	v_exp_f32_e32 v57, v57
	s_waitcnt lgkmcnt(10)
	v_mfma_f32_32x32x16_bf16 v[2:17], v[146:149], v[98:101], v[2:17]
	v_exp_f32_e32 v58, v58
	v_exp_f32_e32 v59, v59
	v_exp_f32_e32 v60, v60
	v_exp_f32_e32 v61, v61
	s_waitcnt lgkmcnt(8)
	v_mfma_f32_32x32x16_bf16 v[18:33], v[146:149], v[86:89], v[18:33]
	v_exp_f32_e32 v62, v62
	v_exp_f32_e32 v63, v63
	v_exp_f32_e32 v64, v64
	v_exp_f32_e32 v65, v65
	s_waitcnt vmcnt(2) lgkmcnt(0)
	s_barrier
	s_andn2_b64 vcc, exec, s[60:61]
	s_cbranch_vccnz .LBB0_884
	s_waitcnt lgkmcnt(0)
	v_add_u32_e32 v98, s92, v212
	ds_read_b128 v[86:89], v98 offset:49248
	ds_read_b128 v[90:93], v98 offset:49216
	ds_read_b128 v[94:97], v98 offset:49184
	ds_read_b128 v[98:101], v98 offset:49152
	s_waitcnt lgkmcnt(3)
	v_pk_mul_f32 v[14:15], v[14:15], v[86:87]
	s_waitcnt lgkmcnt(2)
	v_pk_mul_f32 v[10:11], v[10:11], v[90:91]
	s_waitcnt lgkmcnt(1)
	v_pk_mul_f32 v[6:7], v[6:7], v[94:95]
	v_pk_mul_f32 v[16:17], v[16:17], v[88:89]
	v_pk_mul_f32 v[12:13], v[12:13], v[92:93]
	v_pk_mul_f32 v[8:9], v[8:9], v[96:97]
	s_waitcnt lgkmcnt(0)
	v_pk_mul_f32 v[4:5], v[4:5], v[100:101]
	v_pk_mul_f32 v[2:3], v[2:3], v[98:99]
	v_pk_mul_f32 v[30:31], v[30:31], v[86:87]
	v_pk_mul_f32 v[26:27], v[26:27], v[90:91]
	v_pk_mul_f32 v[22:23], v[22:23], v[94:95]
	v_pk_mul_f32 v[32:33], v[32:33], v[88:89]
	v_pk_mul_f32 v[28:29], v[28:29], v[92:93]
	v_pk_mul_f32 v[24:25], v[24:25], v[96:97]
	v_pk_mul_f32 v[20:21], v[20:21], v[100:101]
	v_pk_mul_f32 v[18:19], v[18:19], v[98:99]

.LBB0_919:
	v_add_u32_e32 v183, s18, v208
	ds_read_b64_tr_b16 v[178:179], v183 offset:24576
	ds_read_b64_tr_b16 v[180:181], v183 offset:25088
	v_mfma_f32_32x32x16_bf16 v[98:113], v[82:85], v[142:145], v[34:49]
	v_add_f32_e32 v86, v66, v67
	v_add_f32_e32 v86, v68, v86
	v_add_f32_e32 v86, v69, v86
	v_add_f32_e32 v86, v70, v86
	v_add_f32_e32 v86, v71, v86
	v_cvt_pk_bf16_f32 v158, v66, v67
	v_cvt_pk_bf16_f32 v159, v68, v69
	ds_read_b64_tr_b16 v[174:175], v183 offset:28672
	ds_read_b64_tr_b16 v[176:177], v183 offset:29184
	v_add_f32_e32 v66, v72, v86
	v_mfma_f32_32x32x16_bf16 v[82:97], v[170:173], v[142:145], v[34:49]
	v_add_f32_e32 v66, v73, v66
	v_add_f32_e32 v66, v74, v66
	v_add_f32_e32 v66, v75, v66
	v_cvt_pk_bf16_f32 v160, v70, v71
	v_cvt_pk_bf16_f32 v161, v72, v73
	ds_read_b64_tr_b16 v[170:171], v183 offset:25600
	ds_read_b64_tr_b16 v[172:173], v183 offset:26112
	v_mfma_f32_32x32x16_bf16 v[98:113], v[166:169], v[138:141], v[98:113]
	v_add_f32_e32 v66, v76, v66
	v_add_f32_e32 v66, v77, v66
	v_add_f32_e32 v66, v78, v66
	v_add_f32_e32 v66, v79, v66
	v_cvt_pk_bf16_f32 v154, v74, v75
	v_cvt_pk_bf16_f32 v155, v76, v77
	ds_read_b64_tr_b16 v[74:75], v183 offset:29696
	ds_read_b64_tr_b16 v[76:77], v183 offset:30208
	v_mfma_f32_32x32x16_bf16 v[82:97], v[162:165], v[138:141], v[82:97]
	v_add_f32_e32 v66, v80, v66
	v_add_f32_e32 v66, v81, v66
	v_add_f32_e32 v66, v50, v66
	v_add_f32_e32 v66, v51, v66
	v_cvt_pk_bf16_f32 v156, v78, v79
	v_cvt_pk_bf16_f32 v157, v80, v81
	ds_read_b64_tr_b16 v[70:71], v183 offset:26624
	ds_read_b64_tr_b16 v[72:73], v183 offset:27136
	v_mfma_f32_32x32x16_bf16 v[98:113], v[126:129], v[134:137], v[98:113]
	v_add_f32_e32 v66, v52, v66
	v_add_f32_e32 v66, v53, v66
	v_add_f32_e32 v66, v54, v66
	v_add_f32_e32 v78, v55, v66
	v_cvt_pk_bf16_f32 v150, v50, v51
	v_cvt_pk_bf16_f32 v151, v52, v53
	ds_read_b64_tr_b16 v[66:67], v183 offset:30720
	ds_read_b64_tr_b16 v[68:69], v183 offset:31232
	v_mfma_f32_32x32x16_bf16 v[82:97], v[122:125], v[134:137], v[82:97]
	v_add_f32_e32 v50, v56, v78
	v_add_f32_e32 v50, v57, v50
	v_add_f32_e32 v50, v58, v50
	v_add_f32_e32 v50, v59, v50
	v_cvt_pk_bf16_f32 v152, v54, v55
	v_cvt_pk_bf16_f32 v153, v56, v57
	ds_read_b64_tr_b16 v[54:55], v183 offset:27648
	ds_read_b64_tr_b16 v[56:57], v183 offset:28160
	v_mfma_f32_32x32x16_bf16 v[98:113], v[118:121], v[130:133], v[98:113]
	v_add_f32_e32 v50, v60, v50
	v_add_f32_e32 v50, v61, v50
	v_add_f32_e32 v50, v62, v50
	v_add_f32_e32 v78, v63, v50
	v_cvt_pk_bf16_f32 v146, v58, v59
	v_cvt_pk_bf16_f32 v147, v60, v61
	ds_read_b64_tr_b16 v[50:51], v183 offset:31744
	ds_read_b64_tr_b16 v[52:53], v183 offset:32256
	v_mfma_f32_32x32x16_bf16 v[82:97], v[114:117], v[130:133], v[82:97]
	v_add_f32_e32 v58, v64, v78
	v_add_f32_e32 v58, v65, v58
	v_add_f32_e32 v60, 0, v58
	v_cvt_pk_bf16_f32 v148, v62, v63
	v_cvt_pk_bf16_f32 v149, v64, v65
	v_lshl_add_u64 v[58:59], v[196:197], 0, s[30:31]
	s_add_i32 s15, s64, s93
	s_mov_b32 s18, m0
	s_mov_b32 m0, s15
	s_nop 0
	global_load_lds_dwordx4 v[58:59], off
	s_mov_b32 m0, s18
	v_lshl_add_u64 v[58:59], v[188:189], 0, s[26:27]
	s_add_i32 s15, s95, s69
	s_mov_b32 s18, m0
	s_mov_b32 m0, s15
	s_nop 0
	global_load_lds_dwordx4 v[58:59], off
	s_mov_b32 m0, s18
	s_waitcnt lgkmcnt(14)
	v_mfma_f32_32x32x16_bf16 v[2:17], v[158:161], v[178:181], v[2:17]
	s_waitcnt lgkmcnt(12)
	v_mfma_f32_32x32x16_bf16 v[18:33], v[158:161], v[174:177], v[18:33]
	v_max_f32_e32 v58, v99, v99
	v_max_f32_e32 v59, v98, v98
	v_max_f32_e32 v58, v59, v58
	v_max3_f32 v59, v100, v101, v83
	v_max3_f32 v58, v58, v82, v84
	v_max3_f32 v58, v58, v85, v102
	v_max3_f32 v59, v59, v104, v105
	v_max3_f32 v58, v58, v103, v86
	v_max3_f32 v59, v59, v88, v89
	v_max3_f32 v58, v58, v87, v106
	v_max3_f32 v59, v59, v108, v109
	v_max3_f32 v58, v58, v107, v90
	v_max3_f32 v59, v59, v92, v93
	v_max3_f32 v58, v58, v91, v110
	v_max3_f32 v59, v59, v112, v113
	v_max3_f32 v58, v58, v111, v94
	v_max3_f32 v59, v59, v96, v97
	v_max3_f32 v58, v58, v95, v59
	v_mov_b32_e32 v59, v58
	s_nop 1
	v_permlane32_swap_b32_e32 v58, v59
	v_max_f32_e32 v59, v59, v59
	v_max_f32_e32 v58, v58, v58
	v_max_f32_e32 v58, v58, v59
	v_cmp_lt_f32_e32 vcc, s83, v58
	s_cmp_lg_u64 vcc, 0
	v_add_f32_e32 v192, v182, v60
	s_cselect_b64 s[60:61], -1, 0
	s_cbranch_vccnz .LBB0_927
.LBB0_920:
	v_exp_f32_e32 v98, v98
	v_exp_f32_e32 v99, v99
	v_exp_f32_e32 v100, v100
	v_exp_f32_e32 v101, v101
	v_exp_f32_e32 v102, v102
	v_exp_f32_e32 v103, v103
	v_exp_f32_e32 v104, v104
	v_exp_f32_e32 v105, v105
	v_add_u32_e32 v62, s95, v210
	ds_read_b128 v[58:61], v62
	ds_read_b128 v[114:117], v62 offset:512
	s_waitcnt lgkmcnt(12)
	v_mfma_f32_32x32x16_bf16 v[2:17], v[154:157], v[170:173], v[2:17]
	v_exp_f32_e32 v106, v106
	v_exp_f32_e32 v107, v107
	v_exp_f32_e32 v108, v108
	v_exp_f32_e32 v109, v109
	ds_read_b128 v[182:185], v62 offset:2048
	ds_read_b128 v[174:177], v62 offset:2560
	s_waitcnt lgkmcnt(12)
	v_mfma_f32_32x32x16_bf16 v[18:33], v[154:157], v[74:77], v[18:33]
	v_exp_f32_e32 v110, v110
	v_exp_f32_e32 v111, v111
	v_exp_f32_e32 v112, v112
	v_exp_f32_e32 v113, v113
	ds_read_b128 v[178:181], v62 offset:4096
	ds_read_b128 v[166:169], v62 offset:4608
	s_waitcnt lgkmcnt(12)
	v_mfma_f32_32x32x16_bf16 v[2:17], v[150:153], v[70:73], v[2:17]
	v_exp_f32_e32 v82, v82
	v_exp_f32_e32 v83, v83
	v_exp_f32_e32 v84, v84
	v_exp_f32_e32 v85, v85
	ds_read_b128 v[170:173], v62 offset:6144
	ds_read_b128 v[162:165], v62 offset:6656
	s_waitcnt lgkmcnt(12)
	v_mfma_f32_32x32x16_bf16 v[18:33], v[150:153], v[66:69], v[18:33]
	v_exp_f32_e32 v86, v86
	v_exp_f32_e32 v87, v87
	v_exp_f32_e32 v88, v88
	v_exp_f32_e32 v89, v89
	s_waitcnt lgkmcnt(10)
	v_mfma_f32_32x32x16_bf16 v[2:17], v[146:149], v[54:57], v[2:17]
	v_exp_f32_e32 v90, v90
	v_exp_f32_e32 v91, v91
	v_exp_f32_e32 v92, v92
	v_exp_f32_e32 v93, v93
	s_waitcnt lgkmcnt(8)
	v_mfma_f32_32x32x16_bf16 v[18:33], v[146:149], v[50:53], v[18:33]
	v_exp_f32_e32 v94, v94
	v_exp_f32_e32 v95, v95
	v_exp_f32_e32 v96, v96
	v_exp_f32_e32 v97, v97
	s_waitcnt vmcnt(2) lgkmcnt(0)
	s_barrier
	s_andn2_b64 vcc, exec, s[60:61]
	s_cbranch_vccnz .LBB0_922
	s_waitcnt lgkmcnt(0)
	v_add_u32_e32 v66, s92, v211
	ds_read_b128 v[50:53], v66 offset:49248
	ds_read_b128 v[54:57], v66 offset:49216
	ds_read_b128 v[62:65], v66 offset:49184
	ds_read_b128 v[66:69], v66 offset:49152
	s_waitcnt lgkmcnt(3)
	v_pk_mul_f32 v[14:15], v[14:15], v[50:51]
	s_waitcnt lgkmcnt(2)
	v_pk_mul_f32 v[10:11], v[10:11], v[54:55]
	s_waitcnt lgkmcnt(1)
	v_pk_mul_f32 v[6:7], v[6:7], v[62:63]
	v_pk_mul_f32 v[16:17], v[16:17], v[52:53]
	v_pk_mul_f32 v[12:13], v[12:13], v[56:57]
	v_pk_mul_f32 v[8:9], v[8:9], v[64:65]
	s_waitcnt lgkmcnt(0)
	v_pk_mul_f32 v[4:5], v[4:5], v[68:69]
	v_pk_mul_f32 v[2:3], v[2:3], v[66:67]
	v_pk_mul_f32 v[30:31], v[30:31], v[50:51]
	v_pk_mul_f32 v[26:27], v[26:27], v[54:55]
	v_pk_mul_f32 v[22:23], v[22:23], v[62:63]
	v_pk_mul_f32 v[32:33], v[32:33], v[52:53]
	v_pk_mul_f32 v[28:29], v[28:29], v[56:57]
	v_pk_mul_f32 v[24:25], v[24:25], v[64:65]
	v_pk_mul_f32 v[20:21], v[20:21], v[68:69]
	v_pk_mul_f32 v[18:19], v[18:19], v[66:67]
.LBB0_922:
	s_add_i32 s15, s95, 0x2000
	s_cmpk_lg_i32 s95, 0x4000
	s_cselect_b32 s65, s15, 0
	v_add_u32_e32 v203, s64, v208
	ds_read_b64_tr_b16 v[126:127], v203 offset:24576
	ds_read_b64_tr_b16 v[128:129], v203 offset:25088
	v_mfma_f32_32x32x16_bf16 v[66:81], v[58:61], v[142:145], v[34:49]
	v_add_f32_e32 v50, v98, v99
	v_add_f32_e32 v50, v100, v50
	v_add_f32_e32 v50, v101, v50
	v_add_f32_e32 v50, v102, v50
	v_add_f32_e32 v50, v103, v50
	v_cvt_pk_bf16_f32 v158, v98, v99
	v_cvt_pk_bf16_f32 v159, v100, v101
	ds_read_b64_tr_b16 v[122:123], v203 offset:28672
	ds_read_b64_tr_b16 v[124:125], v203 offset:29184
	v_add_f32_e32 v50, v104, v50
	v_add_f32_e32 v50, v105, v50
	v_add_f32_e32 v50, v106, v50
	v_add_f32_e32 v98, v107, v50
	v_mfma_f32_32x32x16_bf16 v[50:65], v[114:117], v[142:145], v[34:49]
	v_cvt_pk_bf16_f32 v160, v102, v103
	v_cvt_pk_bf16_f32 v161, v104, v105
	ds_read_b64_tr_b16 v[118:119], v203 offset:25600
	ds_read_b64_tr_b16 v[120:121], v203 offset:26112
	v_mfma_f32_32x32x16_bf16 v[66:81], v[182:185], v[138:141], v[66:81]
	v_add_f32_e32 v98, v108, v98
	v_add_f32_e32 v98, v109, v98
	v_add_f32_e32 v98, v110, v98
	v_add_f32_e32 v98, v111, v98
	v_cvt_pk_bf16_f32 v154, v106, v107
	v_cvt_pk_bf16_f32 v155, v108, v109
	ds_read_b64_tr_b16 v[114:115], v203 offset:29696
	ds_read_b64_tr_b16 v[116:117], v203 offset:30208
	v_mfma_f32_32x32x16_bf16 v[50:65], v[174:177], v[138:141], v[50:65]
	v_add_f32_e32 v98, v112, v98
	v_add_f32_e32 v98, v113, v98
	v_add_f32_e32 v98, v82, v98
	v_add_f32_e32 v98, v83, v98
	v_cvt_pk_bf16_f32 v156, v110, v111
	v_cvt_pk_bf16_f32 v157, v112, v113
	ds_read_b64_tr_b16 v[106:107], v203 offset:26624
	ds_read_b64_tr_b16 v[108:109], v203 offset:27136
	v_mfma_f32_32x32x16_bf16 v[66:81], v[178:181], v[134:137], v[66:81]
	v_add_f32_e32 v98, v84, v98
	v_add_f32_e32 v98, v85, v98
	v_add_f32_e32 v98, v86, v98
	v_add_f32_e32 v98, v87, v98
	v_cvt_pk_bf16_f32 v150, v82, v83
	v_cvt_pk_bf16_f32 v151, v84, v85
	ds_read_b64_tr_b16 v[102:103], v203 offset:30720
	ds_read_b64_tr_b16 v[104:105], v203 offset:31232
	v_mfma_f32_32x32x16_bf16 v[50:65], v[166:169], v[134:137], v[50:65]
	v_add_f32_e32 v82, v88, v98
	v_add_f32_e32 v82, v89, v82
	v_add_f32_e32 v82, v90, v82
	v_add_f32_e32 v82, v91, v82
	v_cvt_pk_bf16_f32 v152, v86, v87
	v_cvt_pk_bf16_f32 v153, v88, v89
	ds_read_b64_tr_b16 v[98:99], v203 offset:27648
	ds_read_b64_tr_b16 v[100:101], v203 offset:28160
	v_mfma_f32_32x32x16_bf16 v[66:81], v[170:173], v[130:133], v[66:81]
	v_add_f32_e32 v82, v92, v82
	v_add_f32_e32 v82, v93, v82
	v_add_f32_e32 v82, v94, v82
	v_add_f32_e32 v82, v95, v82
	v_cvt_pk_bf16_f32 v146, v90, v91
	v_cvt_pk_bf16_f32 v147, v92, v93
	ds_read_b64_tr_b16 v[86:87], v203 offset:31744
	ds_read_b64_tr_b16 v[88:89], v203 offset:32256
	v_mfma_f32_32x32x16_bf16 v[50:65], v[162:165], v[130:133], v[50:65]
	v_add_f32_e32 v82, v96, v82
	v_add_f32_e32 v82, v97, v82
	v_add_f32_e32 v84, 0, v82
	v_cvt_pk_bf16_f32 v148, v94, v95
	v_cvt_pk_bf16_f32 v149, v96, v97
	v_lshl_add_u64 v[82:83], v[196:197], 0, s[34:35]
	s_add_i32 s15, s95, s93
	s_mov_b32 s18, m0
	s_mov_b32 m0, s15
	s_nop 0
	global_load_lds_dwordx4 v[82:83], off
	s_mov_b32 m0, s18
	s_waitcnt lgkmcnt(14)
	v_mfma_f32_32x32x16_bf16 v[2:17], v[158:161], v[126:129], v[2:17]
	s_waitcnt lgkmcnt(12)
	v_mfma_f32_32x32x16_bf16 v[18:33], v[158:161], v[122:125], v[18:33]
	v_max_f32_e32 v82, v67, v67
	v_max_f32_e32 v83, v66, v66
	v_max_f32_e32 v82, v83, v82
	s_nop 1
	v_max3_f32 v83, v68, v69, v51
	v_max3_f32 v82, v82, v50, v52
	v_max3_f32 v82, v82, v53, v70
	v_max3_f32 v83, v83, v72, v73
	v_max3_f32 v82, v82, v71, v54
	v_max3_f32 v83, v83, v56, v57
	v_max3_f32 v82, v82, v55, v74
	v_max3_f32 v83, v83, v76, v77
	v_max3_f32 v82, v82, v75, v58
	v_max3_f32 v83, v83, v60, v61
	v_max3_f32 v82, v82, v59, v78
	v_max3_f32 v83, v83, v80, v81
	v_max3_f32 v82, v82, v79, v62
	v_max3_f32 v83, v83, v64, v65
	v_max3_f32 v82, v82, v63, v83
	v_mov_b32_e32 v83, v82
	s_nop 1
	v_permlane32_swap_b32_e32 v82, v83
	v_max_f32_e32 v83, v83, v83
	v_max_f32_e32 v82, v82, v82
	v_max_f32_e32 v82, v82, v83
	v_lshl_add_u64 v[188:189], v[188:189], 0, s[28:29]
	s_add_i32 s15, s65, s69
	s_mov_b32 s18, m0
	s_mov_b32 m0, s15
	s_nop 0
	global_load_lds_dwordx4 v[188:189], off
	s_mov_b32 m0, s18
	v_cmp_lt_f32_e32 vcc, s83, v82
	s_cmp_lg_u64 vcc, 0
	v_add_f32_e32 v182, v192, v84
	s_cselect_b64 s[60:61], -1, 0
	s_cbranch_vccnz .LBB0_930
.LBB0_923:
	v_exp_f32_e32 v66, v66
	v_exp_f32_e32 v67, v67
	v_exp_f32_e32 v68, v68
	v_exp_f32_e32 v69, v69
	v_exp_f32_e32 v70, v70
	v_exp_f32_e32 v71, v71
	v_exp_f32_e32 v72, v72
	v_exp_f32_e32 v73, v73
	v_add_u32_e32 v90, s65, v210
	ds_read_b128 v[82:85], v90
	ds_read_b128 v[170:173], v90 offset:512
	s_waitcnt lgkmcnt(12)
	v_mfma_f32_32x32x16_bf16 v[2:17], v[154:157], v[118:121], v[2:17]
	v_exp_f32_e32 v74, v74
	v_exp_f32_e32 v75, v75
	v_exp_f32_e32 v76, v76
	v_exp_f32_e32 v77, v77
	ds_read_b128 v[166:169], v90 offset:2048
	ds_read_b128 v[162:165], v90 offset:2560
	s_waitcnt lgkmcnt(12)
	v_mfma_f32_32x32x16_bf16 v[18:33], v[154:157], v[114:117], v[18:33]
	v_exp_f32_e32 v78, v78
	v_exp_f32_e32 v79, v79
	v_exp_f32_e32 v80, v80
	v_exp_f32_e32 v81, v81
	ds_read_b128 v[126:129], v90 offset:4096
	ds_read_b128 v[122:125], v90 offset:4608
	s_waitcnt lgkmcnt(12)
	v_mfma_f32_32x32x16_bf16 v[2:17], v[150:153], v[106:109], v[2:17]
	v_exp_f32_e32 v50, v50
	v_exp_f32_e32 v51, v51
	v_exp_f32_e32 v52, v52
	v_exp_f32_e32 v53, v53
	ds_read_b128 v[118:121], v90 offset:6144
	ds_read_b128 v[114:117], v90 offset:6656
	s_waitcnt lgkmcnt(12)
	v_mfma_f32_32x32x16_bf16 v[18:33], v[150:153], v[102:105], v[18:33]
	v_exp_f32_e32 v54, v54
	v_exp_f32_e32 v55, v55
	v_exp_f32_e32 v56, v56
	v_exp_f32_e32 v57, v57
	s_waitcnt lgkmcnt(10)
	v_mfma_f32_32x32x16_bf16 v[2:17], v[146:149], v[98:101], v[2:17]
	v_exp_f32_e32 v58, v58
	v_exp_f32_e32 v59, v59
	v_exp_f32_e32 v60, v60
	v_exp_f32_e32 v61, v61
	s_waitcnt lgkmcnt(8)
	v_mfma_f32_32x32x16_bf16 v[18:33], v[146:149], v[86:89], v[18:33]
	v_exp_f32_e32 v62, v62
	v_exp_f32_e32 v63, v63
	v_exp_f32_e32 v64, v64
	v_exp_f32_e32 v65, v65
	s_waitcnt vmcnt(2) lgkmcnt(0)
	s_barrier
	s_andn2_b64 vcc, exec, s[60:61]
	s_cbranch_vccnz .LBB0_925
	s_waitcnt lgkmcnt(0)
	v_add_u32_e32 v98, s92, v211
	ds_read_b128 v[86:89], v98 offset:49248
	ds_read_b128 v[90:93], v98 offset:49216
	ds_read_b128 v[94:97], v98 offset:49184
	ds_read_b128 v[98:101], v98 offset:49152
	s_waitcnt lgkmcnt(3)
	v_pk_mul_f32 v[14:15], v[14:15], v[86:87]
	s_waitcnt lgkmcnt(2)
	v_pk_mul_f32 v[10:11], v[10:11], v[90:91]
	s_waitcnt lgkmcnt(1)
	v_pk_mul_f32 v[6:7], v[6:7], v[94:95]
	v_pk_mul_f32 v[16:17], v[16:17], v[88:89]
	v_pk_mul_f32 v[12:13], v[12:13], v[92:93]
	v_pk_mul_f32 v[8:9], v[8:9], v[96:97]
	s_waitcnt lgkmcnt(0)
	v_pk_mul_f32 v[4:5], v[4:5], v[100:101]
	v_pk_mul_f32 v[2:3], v[2:3], v[98:99]
	v_pk_mul_f32 v[30:31], v[30:31], v[86:87]
	v_pk_mul_f32 v[26:27], v[26:27], v[90:91]
	v_pk_mul_f32 v[22:23], v[22:23], v[94:95]
	v_pk_mul_f32 v[32:33], v[32:33], v[88:89]
	v_pk_mul_f32 v[28:29], v[28:29], v[92:93]
	v_pk_mul_f32 v[24:25], v[24:25], v[96:97]
	v_pk_mul_f32 v[20:21], v[20:21], v[100:101]
	v_pk_mul_f32 v[18:19], v[18:19], v[98:99]

.LBB0_2477:
	v_add_u32_e32 v183, s18, v209
	ds_read_b64_tr_b16 v[178:179], v183 offset:24576
	ds_read_b64_tr_b16 v[180:181], v183 offset:25088
	v_mfma_f32_32x32x16_bf16 v[98:113], v[82:85], v[142:145], v[34:49]
	v_add_f32_e32 v86, v66, v67
	v_add_f32_e32 v86, v68, v86
	v_add_f32_e32 v86, v69, v86
	v_add_f32_e32 v86, v70, v86
	v_add_f32_e32 v86, v71, v86
	v_cvt_pk_bf16_f32 v158, v66, v67
	v_cvt_pk_bf16_f32 v159, v68, v69
	ds_read_b64_tr_b16 v[174:175], v183 offset:28672
	ds_read_b64_tr_b16 v[176:177], v183 offset:29184
	v_add_f32_e32 v66, v72, v86
	v_mfma_f32_32x32x16_bf16 v[82:97], v[170:173], v[142:145], v[34:49]
	v_add_f32_e32 v66, v73, v66
	v_add_f32_e32 v66, v74, v66
	v_add_f32_e32 v66, v75, v66
	v_cvt_pk_bf16_f32 v160, v70, v71
	v_cvt_pk_bf16_f32 v161, v72, v73
	ds_read_b64_tr_b16 v[170:171], v183 offset:25600
	ds_read_b64_tr_b16 v[172:173], v183 offset:26112
	v_mfma_f32_32x32x16_bf16 v[98:113], v[166:169], v[138:141], v[98:113]
	v_add_f32_e32 v66, v76, v66
	v_add_f32_e32 v66, v77, v66
	v_add_f32_e32 v66, v78, v66
	v_add_f32_e32 v66, v79, v66
	v_cvt_pk_bf16_f32 v154, v74, v75
	v_cvt_pk_bf16_f32 v155, v76, v77
	ds_read_b64_tr_b16 v[74:75], v183 offset:29696
	ds_read_b64_tr_b16 v[76:77], v183 offset:30208
	v_mfma_f32_32x32x16_bf16 v[82:97], v[162:165], v[138:141], v[82:97]
	v_add_f32_e32 v66, v80, v66
	v_add_f32_e32 v66, v81, v66
	v_add_f32_e32 v66, v50, v66
	v_add_f32_e32 v66, v51, v66
	v_cvt_pk_bf16_f32 v156, v78, v79
	v_cvt_pk_bf16_f32 v157, v80, v81
	ds_read_b64_tr_b16 v[70:71], v183 offset:26624
	ds_read_b64_tr_b16 v[72:73], v183 offset:27136
	v_mfma_f32_32x32x16_bf16 v[98:113], v[126:129], v[134:137], v[98:113]
	v_add_f32_e32 v66, v52, v66
	v_add_f32_e32 v66, v53, v66
	v_add_f32_e32 v66, v54, v66
	v_add_f32_e32 v78, v55, v66
	v_cvt_pk_bf16_f32 v150, v50, v51
	v_cvt_pk_bf16_f32 v151, v52, v53
	ds_read_b64_tr_b16 v[66:67], v183 offset:30720
	ds_read_b64_tr_b16 v[68:69], v183 offset:31232
	v_mfma_f32_32x32x16_bf16 v[82:97], v[122:125], v[134:137], v[82:97]
	v_add_f32_e32 v50, v56, v78
	v_add_f32_e32 v50, v57, v50
	v_add_f32_e32 v50, v58, v50
	v_add_f32_e32 v50, v59, v50
	v_cvt_pk_bf16_f32 v152, v54, v55
	v_cvt_pk_bf16_f32 v153, v56, v57
	ds_read_b64_tr_b16 v[54:55], v183 offset:27648
	ds_read_b64_tr_b16 v[56:57], v183 offset:28160
	v_mfma_f32_32x32x16_bf16 v[98:113], v[118:121], v[130:133], v[98:113]
	v_add_f32_e32 v50, v60, v50
	v_add_f32_e32 v50, v61, v50
	v_add_f32_e32 v50, v62, v50
	v_add_f32_e32 v78, v63, v50
	v_cvt_pk_bf16_f32 v146, v58, v59
	v_cvt_pk_bf16_f32 v147, v60, v61
	ds_read_b64_tr_b16 v[50:51], v183 offset:31744
	ds_read_b64_tr_b16 v[52:53], v183 offset:32256
	v_mfma_f32_32x32x16_bf16 v[82:97], v[114:117], v[130:133], v[82:97]
	v_add_f32_e32 v58, v64, v78
	v_add_f32_e32 v58, v65, v58
	v_add_f32_e32 v60, 0, v58
	v_cvt_pk_bf16_f32 v148, v62, v63
	v_cvt_pk_bf16_f32 v149, v64, v65
	v_lshl_add_u64 v[58:59], v[196:197], 0, s[30:31]
	s_add_i32 s15, s64, s94
	s_mov_b32 s18, m0
	s_mov_b32 m0, s15
	s_nop 0
	global_load_lds_dwordx4 v[58:59], off
	s_mov_b32 m0, s18
	v_lshl_add_u64 v[58:59], v[188:189], 0, s[26:27]
	s_add_i32 s15, s96, s93
	s_mov_b32 s18, m0
	s_mov_b32 m0, s15
	s_nop 0
	global_load_lds_dwordx4 v[58:59], off
	s_mov_b32 m0, s18
	s_waitcnt lgkmcnt(14)
	v_mfma_f32_32x32x16_bf16 v[2:17], v[158:161], v[178:181], v[2:17]
	s_waitcnt lgkmcnt(12)
	v_mfma_f32_32x32x16_bf16 v[18:33], v[158:161], v[174:177], v[18:33]
	v_max_f32_e32 v58, v99, v99
	v_max_f32_e32 v59, v98, v98
	v_max_f32_e32 v58, v59, v58
	v_max3_f32 v59, v100, v101, v83
	v_max3_f32 v58, v58, v82, v84
	v_max3_f32 v58, v58, v85, v102
	v_max3_f32 v59, v59, v104, v105
	v_max3_f32 v58, v58, v103, v86
	v_max3_f32 v59, v59, v88, v89
	v_max3_f32 v58, v58, v87, v106
	v_max3_f32 v59, v59, v108, v109
	v_max3_f32 v58, v58, v107, v90
	v_max3_f32 v59, v59, v92, v93
	v_max3_f32 v58, v58, v91, v110
	v_max3_f32 v59, v59, v112, v113
	v_max3_f32 v58, v58, v111, v94
	v_max3_f32 v59, v59, v96, v97
	v_max3_f32 v58, v58, v95, v59
	v_mov_b32_e32 v59, v58
	s_nop 1
	v_permlane32_swap_b32_e32 v58, v59
	v_max_f32_e32 v59, v59, v59
	v_max_f32_e32 v58, v58, v58
	v_max_f32_e32 v58, v58, v59
	v_cmp_lt_f32_e32 vcc, s82, v58
	s_cmp_lg_u64 vcc, 0
	v_add_f32_e32 v213, v182, v60
	s_cselect_b64 s[60:61], -1, 0
	s_cbranch_vccnz .LBB0_2485
.LBB0_2478:
	v_exp_f32_e32 v98, v98
	v_exp_f32_e32 v99, v99
	v_exp_f32_e32 v100, v100
	v_exp_f32_e32 v101, v101
	v_exp_f32_e32 v102, v102
	v_exp_f32_e32 v103, v103
	v_exp_f32_e32 v104, v104
	v_exp_f32_e32 v105, v105
	v_add_u32_e32 v62, s96, v211
	ds_read_b128 v[58:61], v62
	ds_read_b128 v[114:117], v62 offset:512
	s_waitcnt lgkmcnt(12)
	v_mfma_f32_32x32x16_bf16 v[2:17], v[154:157], v[170:173], v[2:17]
	v_exp_f32_e32 v106, v106
	v_exp_f32_e32 v107, v107
	v_exp_f32_e32 v108, v108
	v_exp_f32_e32 v109, v109
	ds_read_b128 v[182:185], v62 offset:2048
	ds_read_b128 v[174:177], v62 offset:2560
	s_waitcnt lgkmcnt(12)
	v_mfma_f32_32x32x16_bf16 v[18:33], v[154:157], v[74:77], v[18:33]
	v_exp_f32_e32 v110, v110
	v_exp_f32_e32 v111, v111
	v_exp_f32_e32 v112, v112
	v_exp_f32_e32 v113, v113
	ds_read_b128 v[178:181], v62 offset:4096
	ds_read_b128 v[166:169], v62 offset:4608
	s_waitcnt lgkmcnt(12)
	v_mfma_f32_32x32x16_bf16 v[2:17], v[150:153], v[70:73], v[2:17]
	v_exp_f32_e32 v82, v82
	v_exp_f32_e32 v83, v83
	v_exp_f32_e32 v84, v84
	v_exp_f32_e32 v85, v85
	ds_read_b128 v[170:173], v62 offset:6144
	ds_read_b128 v[162:165], v62 offset:6656
	s_waitcnt lgkmcnt(12)
	v_mfma_f32_32x32x16_bf16 v[18:33], v[150:153], v[66:69], v[18:33]
	v_exp_f32_e32 v86, v86
	v_exp_f32_e32 v87, v87
	v_exp_f32_e32 v88, v88
	v_exp_f32_e32 v89, v89
	s_waitcnt lgkmcnt(10)
	v_mfma_f32_32x32x16_bf16 v[2:17], v[146:149], v[54:57], v[2:17]
	v_exp_f32_e32 v90, v90
	v_exp_f32_e32 v91, v91
	v_exp_f32_e32 v92, v92
	v_exp_f32_e32 v93, v93
	s_waitcnt lgkmcnt(8)
	v_mfma_f32_32x32x16_bf16 v[18:33], v[146:149], v[50:53], v[18:33]
	v_exp_f32_e32 v94, v94
	v_exp_f32_e32 v95, v95
	v_exp_f32_e32 v96, v96
	v_exp_f32_e32 v97, v97
	s_waitcnt vmcnt(2) lgkmcnt(0)
	s_barrier
	s_andn2_b64 vcc, exec, s[60:61]
	s_cbranch_vccnz .LBB0_2480
	s_waitcnt lgkmcnt(0)
	v_add_u32_e32 v66, s92, v212
	ds_read_b128 v[50:53], v66 offset:49248
	ds_read_b128 v[54:57], v66 offset:49216
	ds_read_b128 v[62:65], v66 offset:49184
	ds_read_b128 v[66:69], v66 offset:49152
	s_waitcnt lgkmcnt(3)
	v_pk_mul_f32 v[14:15], v[14:15], v[50:51]
	s_waitcnt lgkmcnt(2)
	v_pk_mul_f32 v[10:11], v[10:11], v[54:55]
	s_waitcnt lgkmcnt(1)
	v_pk_mul_f32 v[6:7], v[6:7], v[62:63]
	v_pk_mul_f32 v[16:17], v[16:17], v[52:53]
	v_pk_mul_f32 v[12:13], v[12:13], v[56:57]
	v_pk_mul_f32 v[8:9], v[8:9], v[64:65]
	s_waitcnt lgkmcnt(0)
	v_pk_mul_f32 v[4:5], v[4:5], v[68:69]
	v_pk_mul_f32 v[2:3], v[2:3], v[66:67]
	v_pk_mul_f32 v[30:31], v[30:31], v[50:51]
	v_pk_mul_f32 v[26:27], v[26:27], v[54:55]
	v_pk_mul_f32 v[22:23], v[22:23], v[62:63]
	v_pk_mul_f32 v[32:33], v[32:33], v[52:53]
	v_pk_mul_f32 v[28:29], v[28:29], v[56:57]
	v_pk_mul_f32 v[24:25], v[24:25], v[64:65]
	v_pk_mul_f32 v[20:21], v[20:21], v[68:69]
	v_pk_mul_f32 v[18:19], v[18:19], v[66:67]
.LBB0_2480:
	s_add_i32 s15, s96, 0x2000
	s_cmpk_lg_i32 s96, 0x4000
	s_cselect_b32 s65, s15, 0
	v_add_u32_e32 v214, s64, v209
	ds_read_b64_tr_b16 v[126:127], v214 offset:24576
	ds_read_b64_tr_b16 v[128:129], v214 offset:25088
	v_mfma_f32_32x32x16_bf16 v[66:81], v[58:61], v[142:145], v[34:49]
	v_add_f32_e32 v50, v98, v99
	v_add_f32_e32 v50, v100, v50
	v_add_f32_e32 v50, v101, v50
	v_add_f32_e32 v50, v102, v50
	v_add_f32_e32 v50, v103, v50
	v_cvt_pk_bf16_f32 v158, v98, v99
	v_cvt_pk_bf16_f32 v159, v100, v101
	ds_read_b64_tr_b16 v[122:123], v214 offset:28672
	ds_read_b64_tr_b16 v[124:125], v214 offset:29184
	v_add_f32_e32 v50, v104, v50
	v_add_f32_e32 v50, v105, v50
	v_add_f32_e32 v50, v106, v50
	v_add_f32_e32 v98, v107, v50
	v_mfma_f32_32x32x16_bf16 v[50:65], v[114:117], v[142:145], v[34:49]
	v_cvt_pk_bf16_f32 v160, v102, v103
	v_cvt_pk_bf16_f32 v161, v104, v105
	ds_read_b64_tr_b16 v[118:119], v214 offset:25600
	ds_read_b64_tr_b16 v[120:121], v214 offset:26112
	v_mfma_f32_32x32x16_bf16 v[66:81], v[182:185], v[138:141], v[66:81]
	v_add_f32_e32 v98, v108, v98
	v_add_f32_e32 v98, v109, v98
	v_add_f32_e32 v98, v110, v98
	v_add_f32_e32 v98, v111, v98
	v_cvt_pk_bf16_f32 v154, v106, v107
	v_cvt_pk_bf16_f32 v155, v108, v109
	ds_read_b64_tr_b16 v[114:115], v214 offset:29696
	ds_read_b64_tr_b16 v[116:117], v214 offset:30208
	v_mfma_f32_32x32x16_bf16 v[50:65], v[174:177], v[138:141], v[50:65]
	v_add_f32_e32 v98, v112, v98
	v_add_f32_e32 v98, v113, v98
	v_add_f32_e32 v98, v82, v98
	v_add_f32_e32 v98, v83, v98
	v_cvt_pk_bf16_f32 v156, v110, v111
	v_cvt_pk_bf16_f32 v157, v112, v113
	ds_read_b64_tr_b16 v[106:107], v214 offset:26624
	ds_read_b64_tr_b16 v[108:109], v214 offset:27136
	v_mfma_f32_32x32x16_bf16 v[66:81], v[178:181], v[134:137], v[66:81]
	v_add_f32_e32 v98, v84, v98
	v_add_f32_e32 v98, v85, v98
	v_add_f32_e32 v98, v86, v98
	v_add_f32_e32 v98, v87, v98
	v_cvt_pk_bf16_f32 v150, v82, v83
	v_cvt_pk_bf16_f32 v151, v84, v85
	ds_read_b64_tr_b16 v[102:103], v214 offset:30720
	ds_read_b64_tr_b16 v[104:105], v214 offset:31232
	v_mfma_f32_32x32x16_bf16 v[50:65], v[166:169], v[134:137], v[50:65]
	v_add_f32_e32 v82, v88, v98
	v_add_f32_e32 v82, v89, v82
	v_add_f32_e32 v82, v90, v82
	v_add_f32_e32 v82, v91, v82
	v_cvt_pk_bf16_f32 v152, v86, v87
	v_cvt_pk_bf16_f32 v153, v88, v89
	ds_read_b64_tr_b16 v[98:99], v214 offset:27648
	ds_read_b64_tr_b16 v[100:101], v214 offset:28160
	v_mfma_f32_32x32x16_bf16 v[66:81], v[170:173], v[130:133], v[66:81]
	v_add_f32_e32 v82, v92, v82
	v_add_f32_e32 v82, v93, v82
	v_add_f32_e32 v82, v94, v82
	v_add_f32_e32 v82, v95, v82
	v_cvt_pk_bf16_f32 v146, v90, v91
	v_cvt_pk_bf16_f32 v147, v92, v93
	ds_read_b64_tr_b16 v[86:87], v214 offset:31744
	ds_read_b64_tr_b16 v[88:89], v214 offset:32256
	v_mfma_f32_32x32x16_bf16 v[50:65], v[162:165], v[130:133], v[50:65]
	v_add_f32_e32 v82, v96, v82
	v_add_f32_e32 v82, v97, v82
	v_add_f32_e32 v84, 0, v82
	v_cvt_pk_bf16_f32 v148, v94, v95
	v_cvt_pk_bf16_f32 v149, v96, v97
	v_lshl_add_u64 v[82:83], v[196:197], 0, s[34:35]
	s_add_i32 s15, s96, s94
	s_mov_b32 s18, m0
	s_mov_b32 m0, s15
	s_nop 0
	global_load_lds_dwordx4 v[82:83], off
	s_mov_b32 m0, s18
	s_waitcnt lgkmcnt(14)
	v_mfma_f32_32x32x16_bf16 v[2:17], v[158:161], v[126:129], v[2:17]
	s_waitcnt lgkmcnt(12)
	v_mfma_f32_32x32x16_bf16 v[18:33], v[158:161], v[122:125], v[18:33]
	v_max_f32_e32 v82, v67, v67
	v_max_f32_e32 v83, v66, v66
	v_max_f32_e32 v82, v83, v82
	s_nop 1
	v_max3_f32 v83, v68, v69, v51
	v_max3_f32 v82, v82, v50, v52
	v_max3_f32 v82, v82, v53, v70
	v_max3_f32 v83, v83, v72, v73
	v_max3_f32 v82, v82, v71, v54
	v_max3_f32 v83, v83, v56, v57
	v_max3_f32 v82, v82, v55, v74
	v_max3_f32 v83, v83, v76, v77
	v_max3_f32 v82, v82, v75, v58
	v_max3_f32 v83, v83, v60, v61
	v_max3_f32 v82, v82, v59, v78
	v_max3_f32 v83, v83, v80, v81
	v_max3_f32 v82, v82, v79, v62
	v_max3_f32 v83, v83, v64, v65
	v_max3_f32 v82, v82, v63, v83
	v_mov_b32_e32 v83, v82
	s_nop 1
	v_permlane32_swap_b32_e32 v82, v83
	v_max_f32_e32 v83, v83, v83
	v_max_f32_e32 v82, v82, v82
	v_max_f32_e32 v82, v82, v83
	v_lshl_add_u64 v[188:189], v[188:189], 0, s[28:29]
	s_add_i32 s15, s65, s93
	s_mov_b32 s18, m0
	s_mov_b32 m0, s15
	s_nop 0
	global_load_lds_dwordx4 v[188:189], off
	s_mov_b32 m0, s18
	v_cmp_lt_f32_e32 vcc, s82, v82
	s_cmp_lg_u64 vcc, 0
	v_add_f32_e32 v182, v213, v84
	s_cselect_b64 s[60:61], -1, 0
	s_cbranch_vccnz .LBB0_2488

.LBB0_2518:
	v_add_u32_e32 v183, s18, v208
	ds_read_b64_tr_b16 v[178:179], v183 offset:24576
	ds_read_b64_tr_b16 v[180:181], v183 offset:25088
	v_mfma_f32_32x32x16_bf16 v[98:113], v[82:85], v[142:145], v[34:49]
	v_add_f32_e32 v86, v66, v67
	v_add_f32_e32 v86, v68, v86
	v_add_f32_e32 v86, v69, v86
	v_add_f32_e32 v86, v70, v86
	v_add_f32_e32 v86, v71, v86
	v_cvt_pk_bf16_f32 v158, v66, v67
	v_cvt_pk_bf16_f32 v159, v68, v69
	ds_read_b64_tr_b16 v[174:175], v183 offset:28672
	ds_read_b64_tr_b16 v[176:177], v183 offset:29184
	v_add_f32_e32 v66, v72, v86
	v_mfma_f32_32x32x16_bf16 v[82:97], v[170:173], v[142:145], v[34:49]
	v_add_f32_e32 v66, v73, v66
	v_add_f32_e32 v66, v74, v66
	v_add_f32_e32 v66, v75, v66
	v_cvt_pk_bf16_f32 v160, v70, v71
	v_cvt_pk_bf16_f32 v161, v72, v73
	ds_read_b64_tr_b16 v[170:171], v183 offset:25600
	ds_read_b64_tr_b16 v[172:173], v183 offset:26112
	v_mfma_f32_32x32x16_bf16 v[98:113], v[166:169], v[138:141], v[98:113]
	v_add_f32_e32 v66, v76, v66
	v_add_f32_e32 v66, v77, v66
	v_add_f32_e32 v66, v78, v66
	v_add_f32_e32 v66, v79, v66
	v_cvt_pk_bf16_f32 v154, v74, v75
	v_cvt_pk_bf16_f32 v155, v76, v77
	ds_read_b64_tr_b16 v[74:75], v183 offset:29696
	ds_read_b64_tr_b16 v[76:77], v183 offset:30208
	v_mfma_f32_32x32x16_bf16 v[82:97], v[162:165], v[138:141], v[82:97]
	v_add_f32_e32 v66, v80, v66
	v_add_f32_e32 v66, v81, v66
	v_add_f32_e32 v66, v50, v66
	v_add_f32_e32 v66, v51, v66
	v_cvt_pk_bf16_f32 v156, v78, v79
	v_cvt_pk_bf16_f32 v157, v80, v81
	ds_read_b64_tr_b16 v[70:71], v183 offset:26624
	ds_read_b64_tr_b16 v[72:73], v183 offset:27136
	v_mfma_f32_32x32x16_bf16 v[98:113], v[126:129], v[134:137], v[98:113]
	v_add_f32_e32 v66, v52, v66
	v_add_f32_e32 v66, v53, v66
	v_add_f32_e32 v66, v54, v66
	v_add_f32_e32 v78, v55, v66
	v_cvt_pk_bf16_f32 v150, v50, v51
	v_cvt_pk_bf16_f32 v151, v52, v53
	ds_read_b64_tr_b16 v[66:67], v183 offset:30720
	ds_read_b64_tr_b16 v[68:69], v183 offset:31232
	v_mfma_f32_32x32x16_bf16 v[82:97], v[122:125], v[134:137], v[82:97]
	v_add_f32_e32 v50, v56, v78
	v_add_f32_e32 v50, v57, v50
	v_add_f32_e32 v50, v58, v50
	v_add_f32_e32 v50, v59, v50
	v_cvt_pk_bf16_f32 v152, v54, v55
	v_cvt_pk_bf16_f32 v153, v56, v57
	ds_read_b64_tr_b16 v[54:55], v183 offset:27648
	ds_read_b64_tr_b16 v[56:57], v183 offset:28160
	v_mfma_f32_32x32x16_bf16 v[98:113], v[118:121], v[130:133], v[98:113]
	v_add_f32_e32 v50, v60, v50
	v_add_f32_e32 v50, v61, v50
	v_add_f32_e32 v50, v62, v50
	v_add_f32_e32 v78, v63, v50
	v_cvt_pk_bf16_f32 v146, v58, v59
	v_cvt_pk_bf16_f32 v147, v60, v61
	ds_read_b64_tr_b16 v[50:51], v183 offset:31744
	ds_read_b64_tr_b16 v[52:53], v183 offset:32256
	v_mfma_f32_32x32x16_bf16 v[82:97], v[114:117], v[130:133], v[82:97]
	v_add_f32_e32 v58, v64, v78
	v_add_f32_e32 v58, v65, v58
	v_add_f32_e32 v60, 0, v58
	v_cvt_pk_bf16_f32 v148, v62, v63
	v_cvt_pk_bf16_f32 v149, v64, v65
	v_lshl_add_u64 v[58:59], v[196:197], 0, s[30:31]
	s_add_i32 s15, s64, s93
	s_mov_b32 s18, m0
	s_mov_b32 m0, s15
	s_nop 0
	global_load_lds_dwordx4 v[58:59], off
	s_mov_b32 m0, s18
	v_lshl_add_u64 v[58:59], v[188:189], 0, s[26:27]
	s_add_i32 s15, s95, s69
	s_mov_b32 s18, m0
	s_mov_b32 m0, s15
	s_nop 0
	global_load_lds_dwordx4 v[58:59], off
	s_mov_b32 m0, s18
	s_waitcnt lgkmcnt(14)
	v_mfma_f32_32x32x16_bf16 v[2:17], v[158:161], v[178:181], v[2:17]
	s_waitcnt lgkmcnt(12)
	v_mfma_f32_32x32x16_bf16 v[18:33], v[158:161], v[174:177], v[18:33]
	v_max_f32_e32 v58, v99, v99
	v_max_f32_e32 v59, v98, v98
	v_max_f32_e32 v58, v59, v58
	v_max3_f32 v59, v100, v101, v83
	v_max3_f32 v58, v58, v82, v84
	v_max3_f32 v58, v58, v85, v102
	v_max3_f32 v59, v59, v104, v105
	v_max3_f32 v58, v58, v103, v86
	v_max3_f32 v59, v59, v88, v89
	v_max3_f32 v58, v58, v87, v106
	v_max3_f32 v59, v59, v108, v109
	v_max3_f32 v58, v58, v107, v90
	v_max3_f32 v59, v59, v92, v93
	v_max3_f32 v58, v58, v91, v110
	v_max3_f32 v59, v59, v112, v113
	v_max3_f32 v58, v58, v111, v94
	v_max3_f32 v59, v59, v96, v97
	v_max3_f32 v58, v58, v95, v59
	v_mov_b32_e32 v59, v58
	s_nop 1
	v_permlane32_swap_b32_e32 v58, v59
	v_max_f32_e32 v59, v59, v59
	v_max_f32_e32 v58, v58, v58
	v_max_f32_e32 v58, v58, v59
	v_cmp_lt_f32_e32 vcc, s82, v58
	s_cmp_lg_u64 vcc, 0
	v_add_f32_e32 v192, v182, v60
	s_cselect_b64 s[60:61], -1, 0
	s_cbranch_vccnz .LBB0_2526

.LBB0_2521:
	s_add_i32 s15, s95, 0x2000
	s_cmpk_lg_i32 s95, 0x4000
	s_cselect_b32 s65, s15, 0
	v_add_u32_e32 v203, s64, v208
	ds_read_b64_tr_b16 v[126:127], v203 offset:24576
	ds_read_b64_tr_b16 v[128:129], v203 offset:25088
	v_mfma_f32_32x32x16_bf16 v[66:81], v[58:61], v[142:145], v[34:49]
	v_add_f32_e32 v50, v98, v99
	v_add_f32_e32 v50, v100, v50
	v_add_f32_e32 v50, v101, v50
	v_add_f32_e32 v50, v102, v50
	v_add_f32_e32 v50, v103, v50
	v_cvt_pk_bf16_f32 v158, v98, v99
	v_cvt_pk_bf16_f32 v159, v100, v101
	ds_read_b64_tr_b16 v[122:123], v203 offset:28672
	ds_read_b64_tr_b16 v[124:125], v203 offset:29184
	v_add_f32_e32 v50, v104, v50
	v_add_f32_e32 v50, v105, v50
	v_add_f32_e32 v50, v106, v50
	v_add_f32_e32 v98, v107, v50
	v_mfma_f32_32x32x16_bf16 v[50:65], v[114:117], v[142:145], v[34:49]
	v_cvt_pk_bf16_f32 v160, v102, v103
	v_cvt_pk_bf16_f32 v161, v104, v105
	ds_read_b64_tr_b16 v[118:119], v203 offset:25600
	ds_read_b64_tr_b16 v[120:121], v203 offset:26112
	v_mfma_f32_32x32x16_bf16 v[66:81], v[182:185], v[138:141], v[66:81]
	v_add_f32_e32 v98, v108, v98
	v_add_f32_e32 v98, v109, v98
	v_add_f32_e32 v98, v110, v98
	v_add_f32_e32 v98, v111, v98
	v_cvt_pk_bf16_f32 v154, v106, v107
	v_cvt_pk_bf16_f32 v155, v108, v109
	ds_read_b64_tr_b16 v[114:115], v203 offset:29696
	ds_read_b64_tr_b16 v[116:117], v203 offset:30208
	v_mfma_f32_32x32x16_bf16 v[50:65], v[174:177], v[138:141], v[50:65]
	v_add_f32_e32 v98, v112, v98
	v_add_f32_e32 v98, v113, v98
	v_add_f32_e32 v98, v82, v98
	v_add_f32_e32 v98, v83, v98
	v_cvt_pk_bf16_f32 v156, v110, v111
	v_cvt_pk_bf16_f32 v157, v112, v113
	ds_read_b64_tr_b16 v[106:107], v203 offset:26624
	ds_read_b64_tr_b16 v[108:109], v203 offset:27136
	v_mfma_f32_32x32x16_bf16 v[66:81], v[178:181], v[134:137], v[66:81]
	v_add_f32_e32 v98, v84, v98
	v_add_f32_e32 v98, v85, v98
	v_add_f32_e32 v98, v86, v98
	v_add_f32_e32 v98, v87, v98
	v_cvt_pk_bf16_f32 v150, v82, v83
	v_cvt_pk_bf16_f32 v151, v84, v85
	ds_read_b64_tr_b16 v[102:103], v203 offset:30720
	ds_read_b64_tr_b16 v[104:105], v203 offset:31232
	v_mfma_f32_32x32x16_bf16 v[50:65], v[166:169], v[134:137], v[50:65]
	v_add_f32_e32 v82, v88, v98
	v_add_f32_e32 v82, v89, v82
	v_add_f32_e32 v82, v90, v82
	v_add_f32_e32 v82, v91, v82
	v_cvt_pk_bf16_f32 v152, v86, v87
	v_cvt_pk_bf16_f32 v153, v88, v89
	ds_read_b64_tr_b16 v[98:99], v203 offset:27648
	ds_read_b64_tr_b16 v[100:101], v203 offset:28160
	v_mfma_f32_32x32x16_bf16 v[66:81], v[170:173], v[130:133], v[66:81]
	v_add_f32_e32 v82, v92, v82
	v_add_f32_e32 v82, v93, v82
	v_add_f32_e32 v82, v94, v82
	v_add_f32_e32 v82, v95, v82
	v_cvt_pk_bf16_f32 v146, v90, v91
	v_cvt_pk_bf16_f32 v147, v92, v93
	ds_read_b64_tr_b16 v[86:87], v203 offset:31744
	ds_read_b64_tr_b16 v[88:89], v203 offset:32256
	v_mfma_f32_32x32x16_bf16 v[50:65], v[162:165], v[130:133], v[50:65]
	v_add_f32_e32 v82, v96, v82
	v_add_f32_e32 v82, v97, v82
	v_add_f32_e32 v84, 0, v82
	v_cvt_pk_bf16_f32 v148, v94, v95
	v_cvt_pk_bf16_f32 v149, v96, v97
	v_lshl_add_u64 v[82:83], v[196:197], 0, s[34:35]
	s_add_i32 s15, s95, s93
	s_mov_b32 s18, m0
	s_mov_b32 m0, s15
	s_nop 0
	global_load_lds_dwordx4 v[82:83], off
	s_mov_b32 m0, s18
	s_waitcnt lgkmcnt(14)
	v_mfma_f32_32x32x16_bf16 v[2:17], v[158:161], v[126:129], v[2:17]
	s_waitcnt lgkmcnt(12)
	v_mfma_f32_32x32x16_bf16 v[18:33], v[158:161], v[122:125], v[18:33]
	v_max_f32_e32 v82, v67, v67
	v_max_f32_e32 v83, v66, v66
	v_max_f32_e32 v82, v83, v82
	s_nop 1
	v_max3_f32 v83, v68, v69, v51
	v_max3_f32 v82, v82, v50, v52
	v_max3_f32 v82, v82, v53, v70
	v_max3_f32 v83, v83, v72, v73
	v_max3_f32 v82, v82, v71, v54
	v_max3_f32 v83, v83, v56, v57
	v_max3_f32 v82, v82, v55, v74
	v_max3_f32 v83, v83, v76, v77
	v_max3_f32 v82, v82, v75, v58
	v_max3_f32 v83, v83, v60, v61
	v_max3_f32 v82, v82, v59, v78
	v_max3_f32 v83, v83, v80, v81
	v_max3_f32 v82, v82, v79, v62
	v_max3_f32 v83, v83, v64, v65
	v_max3_f32 v82, v82, v63, v83
	v_mov_b32_e32 v83, v82
	s_nop 1
	v_permlane32_swap_b32_e32 v82, v83
	v_max_f32_e32 v83, v83, v83
	v_max_f32_e32 v82, v82, v82
	v_max_f32_e32 v82, v82, v83
	v_lshl_add_u64 v[188:189], v[188:189], 0, s[28:29]
	s_add_i32 s15, s65, s69
	s_mov_b32 s18, m0
	s_mov_b32 m0, s15
	s_nop 0
	global_load_lds_dwordx4 v[188:189], off
	s_mov_b32 m0, s18
	v_cmp_lt_f32_e32 vcc, s82, v82
	s_cmp_lg_u64 vcc, 0
	v_add_f32_e32 v182, v192, v84
	s_cselect_b64 s[60:61], -1, 0
	s_cbranch_vccnz .LBB0_2529
